# LDS bank conflicts: sigmoid tile rows padded 96->97 floats (MFMA A-fragment ds_read_b32 was 16-way conflicted)
# speedup vs baseline: 1.0127x; 1.0127x over previous
; __device__ __forceinline__ float bf2f(u16 v) { return __uint_as_float(((unsigned)v) << 16); }
; __device__ __forceinline__ float sigmoidf_(float x) { return 1.f / (1.f + __expf(-x)); }
; __device__ void phase_combine(const P& p, int l, int ntok, float* lds) {
;     ...
;     for (int e = tid; e < 16 * 96; e += NTHR) {
;       int i = e / 96, m = e % 96;
;       sig[e] = sigmoidf_(bf2f(p.projb[(size_t)(r0 + i) * PROJP + O_RG + m]));
;     }
;     __syncthreads();
;     ...
; #pragma unroll
;         for (int m = 0; m < 96; m += 4) {
; #pragma unroll
;           for (int i = 0; i < 4; ++i) {
;             float4 s = *reinterpret_cast<const float4*>(sig + (i0 + i) * 96 + m);
;             gate[i] += s.x * g2r[m] + s.y * g2r[m + 1] + s.z * g2r[m + 2] + s.w * g2r[m + 3];
;           }
;         }
.LBB0_92:
	s_mov_b32 s20, 0x2aaaaaab
	v_mul_hi_i32 v18, v0, s20
	v_lshrrev_b32_e32 v19, 31, v18
	v_ashrrev_i32_e32 v18, 4, v18
	v_add_u32_e32 v20, v18, v19
	s_movk_i32 s20, 0xffa0
	v_mov_b64_e32 v[2:3], s[94:95]
	v_mad_u64_u32 v[18:19], s[22:23], v20, s20, v[0:1]
	v_lshlrev_b32_e32 v244, 2, v20
	v_add_u32_e32 v20, s56, v20
	v_ashrrev_i32_e32 v19, 31, v18
	v_mad_i64_i32 v[2:3], s[22:23], v20, s33, v[2:3]
	v_lshl_add_u64 v[2:3], v[18:19], 1, v[2:3]
	v_add_co_u32_e32 v2, vcc, s75, v2
	s_nop 1
	v_addc_co_u32_e32 v3, vcc, 0, v3, vcc
	global_load_ushort v241, v[2:3], off offset:1216
	v_add_u32_e32 v0, 0x200, v0
	s_mov_b32 s20, 0x2aaaaaab
	v_mul_hi_i32 v18, v0, s20
	v_lshrrev_b32_e32 v19, 31, v18
	v_ashrrev_i32_e32 v18, 4, v18
	v_add_u32_e32 v20, v18, v19
	s_movk_i32 s20, 0xffa0
	v_mov_b64_e32 v[2:3], s[94:95]
	v_mad_u64_u32 v[18:19], s[22:23], v20, s20, v[0:1]
	v_lshlrev_b32_e32 v245, 2, v20
	v_add_u32_e32 v20, s56, v20
	v_ashrrev_i32_e32 v19, 31, v18
	v_mad_i64_i32 v[2:3], s[22:23], v20, s33, v[2:3]
	v_lshl_add_u64 v[2:3], v[18:19], 1, v[2:3]
	v_add_co_u32_e32 v2, vcc, s75, v2
	s_nop 1
	v_addc_co_u32_e32 v3, vcc, 0, v3, vcc
	global_load_ushort v242, v[2:3], off offset:1216
	v_add_u32_e32 v0, 0x200, v0
	s_mov_b32 s20, 0x2aaaaaab
	v_mul_hi_i32 v18, v0, s20
	v_lshrrev_b32_e32 v19, 31, v18
	v_ashrrev_i32_e32 v18, 4, v18
	v_add_u32_e32 v20, v18, v19
	s_movk_i32 s20, 0xffa0
	v_mov_b64_e32 v[2:3], s[94:95]
	v_mad_u64_u32 v[18:19], s[22:23], v20, s20, v[0:1]
	v_lshlrev_b32_e32 v246, 2, v20
	v_add_u32_e32 v20, s56, v20
	v_ashrrev_i32_e32 v19, 31, v18
	v_mad_i64_i32 v[2:3], s[22:23], v20, s33, v[2:3]
	v_lshl_add_u64 v[2:3], v[18:19], 1, v[2:3]
	v_add_co_u32_e32 v2, vcc, s75, v2
	s_nop 1
	v_addc_co_u32_e32 v3, vcc, 0, v3, vcc
	global_load_ushort v243, v[2:3], off offset:1216
	v_add_u32_e32 v0, 0x200, v0
	s_waitcnt vmcnt(0)
	v_lshlrev_b32_e32 v241, 16, v241
	v_mul_f32_e32 v241, 0xbfb8aa3b, v241
	v_exp_f32_e32 v241, v241
	v_lshlrev_b32_e32 v242, 16, v242
	v_mul_f32_e32 v242, 0xbfb8aa3b, v242
	v_exp_f32_e32 v242, v242
	v_lshlrev_b32_e32 v243, 16, v243
	v_mul_f32_e32 v243, 0xbfb8aa3b, v243
	v_exp_f32_e32 v243, v243
	v_add_f32_e32 v241, 1.0, v241
	v_add_f32_e32 v242, 1.0, v242
	v_add_f32_e32 v243, 1.0, v243
	v_rcp_f32_e32 v241, v241
	v_rcp_f32_e32 v242, v242
	v_rcp_f32_e32 v243, v243
	s_nop 0
	v_add_u32_e32 v244, v1, v244
	ds_write_b32 v244, v241
	v_add_u32_e32 v1, 0x800, v1
	v_add_u32_e32 v245, v1, v245
	ds_write_b32 v245, v242
	v_add_u32_e32 v1, 0x800, v1
	v_add_u32_e32 v246, v1, v246
	ds_write_b32 v246, v243
	v_add_u32_e32 v1, 0x800, v1
.LBB0_93:
	s_or_b64 exec, exec, s[0:1]
	s_cmpk_lt_i32 s55, 0x400
	s_movk_i32 s0, 0xfff
	s_cselect_b32 s57, s0, 0xff
	v_readlane_b32 s34, v240, 12
	v_readlane_b32 s62, v240, 14
	s_cselect_b32 s58, 63, 0xff
	s_and_b32 s59, s57, s56
	s_mov_b32 s60, 0
	v_readlane_b32 s35, v240, 13
	v_readlane_b32 s63, v240, 15
	s_mov_b32 s33, 0x800000
	s_movk_i32 s61, 0x3600
	s_mov_b32 s66, 0x88000
	s_mov_b64 s[68:69], 0x3040
	s_waitcnt lgkmcnt(0)
	s_barrier
	v_readfirstlane_b32 s98, v168
	s_lshr_b32 s98, s98, 6
	s_cmp_lt_u32 s98, 4
	s_cbranch_scc0 .Lmf_skip1
	v_and_b32_e32 v241, 15, v168
	v_bfe_u32 v242, v168, 4, 2
	v_mul_u32_u24_e32 v241, 0x184, v241
	v_mul_u32_u24_e32 v243, 0x1fc0, v242
	v_lshl_add_u32 v241, v242, 2, v241
	v_lshl_add_u32 v243, v168, 2, v243
	ds_read_b32 v244, v241
	ds_read_b32 v245, v241 offset:16
	ds_read_b32 v246, v241 offset:32
	ds_read_b32 v247, v241 offset:48
	ds_read_b32 v248, v241 offset:64
	ds_read_b32 v249, v241 offset:80
	ds_read_b32 v250, v241 offset:96
	ds_read_b32 v251, v241 offset:112
	ds_read_b32 v252, v241 offset:128
	ds_read_b32 v253, v241 offset:144
	ds_read_b32 v254, v241 offset:160
	ds_read_b32 v255, v241 offset:176
	s_waitcnt lgkmcnt(0)
	v_mfma_f32_16x16x4_f32 v[220:223], v244, v90, 0
	v_mfma_f32_16x16x4_f32 v[220:223], v245, v33, v[220:223]
	v_mfma_f32_16x16x4_f32 v[220:223], v246, v80, v[220:223]
	v_mfma_f32_16x16x4_f32 v[220:223], v247, v83, v[220:223]
	v_mfma_f32_16x16x4_f32 v[220:223], v248, v86, v[220:223]
	v_mfma_f32_16x16x4_f32 v[220:223], v249, v89, v[220:223]
	v_mfma_f32_16x16x4_f32 v[220:223], v250, v25, v[220:223]
	v_mfma_f32_16x16x4_f32 v[220:223], v251, v96, v[220:223]
	v_mfma_f32_16x16x4_f32 v[220:223], v252, v97, v[220:223]
	v_mfma_f32_16x16x4_f32 v[220:223], v253, v98, v[220:223]
	v_mfma_f32_16x16x4_f32 v[220:223], v254, v99, v[220:223]
	v_mfma_f32_16x16x4_f32 v[220:223], v255, v100, v[220:223]
	v_mfma_f32_16x16x4_f32 v[224:227], v244, v91, 0
	v_mfma_f32_16x16x4_f32 v[224:227], v245, v78, v[224:227]
	v_mfma_f32_16x16x4_f32 v[224:227], v246, v81, v[224:227]
	v_mfma_f32_16x16x4_f32 v[224:227], v247, v84, v[224:227]
	v_mfma_f32_16x16x4_f32 v[224:227], v248, v87, v[224:227]
	v_mfma_f32_16x16x4_f32 v[224:227], v249, v26, v[224:227]
	v_mfma_f32_16x16x4_f32 v[224:227], v250, v30, v[224:227]
	v_mfma_f32_16x16x4_f32 v[224:227], v251, v34, v[224:227]
	v_mfma_f32_16x16x4_f32 v[224:227], v252, v38, v[224:227]
	v_mfma_f32_16x16x4_f32 v[224:227], v253, v42, v[224:227]
	v_mfma_f32_16x16x4_f32 v[224:227], v254, v46, v[224:227]
	v_mfma_f32_16x16x4_f32 v[224:227], v255, v50, v[224:227]
	v_mfma_f32_16x16x4_f32 v[228:231], v244, v32, 0
	v_mfma_f32_16x16x4_f32 v[228:231], v245, v79, v[228:231]
	v_mfma_f32_16x16x4_f32 v[228:231], v246, v82, v[228:231]
	v_mfma_f32_16x16x4_f32 v[228:231], v247, v85, v[228:231]
	v_mfma_f32_16x16x4_f32 v[228:231], v248, v88, v[228:231]
	v_mfma_f32_16x16x4_f32 v[228:231], v249, v27, v[228:231]
	v_mfma_f32_16x16x4_f32 v[228:231], v250, v31, v[228:231]
	v_mfma_f32_16x16x4_f32 v[228:231], v251, v35, v[228:231]
	v_mfma_f32_16x16x4_f32 v[228:231], v252, v39, v[228:231]
	v_mfma_f32_16x16x4_f32 v[228:231], v253, v43, v[228:231]
	v_mfma_f32_16x16x4_f32 v[228:231], v254, v47, v[228:231]
	v_mfma_f32_16x16x4_f32 v[228:231], v255, v51, v[228:231]
	v_mfma_f32_16x16x4_f32 v[232:235], v244, v92, 0
	v_mfma_f32_16x16x4_f32 v[232:235], v245, v93, v[232:235]
	v_mfma_f32_16x16x4_f32 v[232:235], v246, v11, v[232:235]
	v_mfma_f32_16x16x4_f32 v[232:235], v247, v94, v[232:235]
	v_mfma_f32_16x16x4_f32 v[232:235], v248, v95, v[232:235]
	v_mfma_f32_16x16x4_f32 v[232:235], v249, v24, v[232:235]
	v_mfma_f32_16x16x4_f32 v[232:235], v250, v103, v[232:235]
	v_mfma_f32_16x16x4_f32 v[232:235], v251, v28, v[232:235]
	v_mfma_f32_16x16x4_f32 v[232:235], v252, v29, v[232:235]
	v_mfma_f32_16x16x4_f32 v[232:235], v253, v36, v[232:235]
	v_mfma_f32_16x16x4_f32 v[232:235], v254, v37, v[232:235]
	v_mfma_f32_16x16x4_f32 v[232:235], v255, v40, v[232:235]
	ds_read_b32 v244, v241 offset:192
	ds_read_b32 v245, v241 offset:208
	ds_read_b32 v246, v241 offset:224
	ds_read_b32 v247, v241 offset:240
	ds_read_b32 v248, v241 offset:256
	ds_read_b32 v249, v241 offset:272
	ds_read_b32 v250, v241 offset:288
	ds_read_b32 v251, v241 offset:304
	ds_read_b32 v252, v241 offset:320
	ds_read_b32 v253, v241 offset:336
	ds_read_b32 v254, v241 offset:352
	ds_read_b32 v255, v241 offset:368
	s_waitcnt lgkmcnt(0)
; __device__ void phase_combine(const P& p, int l, int ntok, float* lds) {
;     ...
;       for (int i = 0; i < 4; ++i) {
;         int row = r0 + i0 + i, t = tb + i0 + i;
;         y0[i] = or0[(size_t)row * 512 + tid]; y1[i] = or1[(size_t)row * 512 + tid];
;         const u16* pv = p.projb + (size_t)row * PROJP + O_RKV + 1024 + tid;
;         vc[i] = pv[0]; vp[i] = pv[t > 0 ? -PROJP : 0]; vn[i] = pv[t < T - 1 ? PROJP : 0];
;         sf[i] = p.sbon[(size_t)row * 8 + wv]; sb[i] = p.sbon[(size_t)NT * 8 + (size_t)row * 8 + wv];
;         size_t ob = (size_t)row * 512 + hh * 128 + lane;
;         a0[i] = om0[ob]; a1[i] = om1[ob]; a2[i] = om0[ob + 64]; a3[i] = om1[ob + 64];
;         const u16* pg = p.projb + (size_t)row * PROJP + gch;
;         g0r[i] = pg[0]; g1r[i] = pg[64];
;         cbr[i] = p.projb[(size_t)row * PROJP + O_CB + tid];
;       }
;     ...
; #pragma unroll
;         for (int m = 0; m < 96; m += 4) {
; #pragma unroll
;           for (int i = 0; i < 4; ++i) {
;             float4 s = *reinterpret_cast<const float4*>(sig + (i0 + i) * 96 + m);
;             gate[i] += s.x * g2r[m] + s.y * g2r[m + 1] + s.z * g2r[m + 2] + s.w * g2r[m + 3];
;           }
;         }
	v_mfma_f32_16x16x4_f32 v[220:223], v244, v101, v[220:223]
	v_mfma_f32_16x16x4_f32 v[220:223], v245, v102, v[220:223]
	v_mfma_f32_16x16x4_f32 v[220:223], v246, v45, v[220:223]
	v_mfma_f32_16x16x4_f32 v[220:223], v247, v52, v[220:223]
	v_mfma_f32_16x16x4_f32 v[220:223], v248, v59, v[220:223]
	v_mfma_f32_16x16x4_f32 v[220:223], v249, v66, v[220:223]
	v_mfma_f32_16x16x4_f32 v[220:223], v250, v71, v[220:223]
	v_mfma_f32_16x16x4_f32 v[220:223], v251, v104, v[220:223]
	v_mfma_f32_16x16x4_f32 v[220:223], v252, v107, v[220:223]
	v_mfma_f32_16x16x4_f32 v[220:223], v253, v110, v[220:223]
	v_mfma_f32_16x16x4_f32 v[220:223], v254, v76, v[220:223]
	v_mfma_f32_16x16x4_f32 v[220:223], v255, v114, v[220:223]
	v_mfma_f32_16x16x4_f32 v[224:227], v244, v56, v[224:227]
	v_mfma_f32_16x16x4_f32 v[224:227], v245, v60, v[224:227]
	v_mfma_f32_16x16x4_f32 v[224:227], v246, v48, v[224:227]
	v_mfma_f32_16x16x4_f32 v[224:227], v247, v53, v[224:227]
	v_mfma_f32_16x16x4_f32 v[224:227], v248, v64, v[224:227]
	v_mfma_f32_16x16x4_f32 v[224:227], v249, v67, v[224:227]
	v_mfma_f32_16x16x4_f32 v[224:227], v250, v74, v[224:227]
	v_mfma_f32_16x16x4_f32 v[224:227], v251, v105, v[224:227]
	v_mfma_f32_16x16x4_f32 v[224:227], v252, v108, v[224:227]
	v_mfma_f32_16x16x4_f32 v[224:227], v253, v111, v[224:227]
	v_mfma_f32_16x16x4_f32 v[224:227], v254, v77, v[224:227]
	v_mfma_f32_16x16x4_f32 v[224:227], v255, v115, v[224:227]
	v_mfma_f32_16x16x4_f32 v[228:231], v244, v57, v[228:231]
	v_mfma_f32_16x16x4_f32 v[228:231], v245, v61, v[228:231]
	v_mfma_f32_16x16x4_f32 v[228:231], v246, v49, v[228:231]
	v_mfma_f32_16x16x4_f32 v[228:231], v247, v58, v[228:231]
	v_mfma_f32_16x16x4_f32 v[228:231], v248, v65, v[228:231]
	v_mfma_f32_16x16x4_f32 v[228:231], v249, v70, v[228:231]
	v_mfma_f32_16x16x4_f32 v[228:231], v250, v75, v[228:231]
	v_mfma_f32_16x16x4_f32 v[228:231], v251, v106, v[228:231]
	v_mfma_f32_16x16x4_f32 v[228:231], v252, v109, v[228:231]
	v_mfma_f32_16x16x4_f32 v[228:231], v253, v112, v[228:231]
	v_mfma_f32_16x16x4_f32 v[228:231], v254, v113, v[228:231]
	v_mfma_f32_16x16x4_f32 v[228:231], v255, v117, v[228:231]
	v_mfma_f32_16x16x4_f32 v[232:235], v244, v41, v[232:235]
	v_mfma_f32_16x16x4_f32 v[232:235], v245, v44, v[232:235]
	v_mfma_f32_16x16x4_f32 v[232:235], v246, v54, v[232:235]
	v_mfma_f32_16x16x4_f32 v[232:235], v247, v55, v[232:235]
	v_mfma_f32_16x16x4_f32 v[232:235], v248, v62, v[232:235]
	v_mfma_f32_16x16x4_f32 v[232:235], v249, v63, v[232:235]
	v_mfma_f32_16x16x4_f32 v[232:235], v250, v68, v[232:235]
	v_mfma_f32_16x16x4_f32 v[232:235], v251, v69, v[232:235]
	v_mfma_f32_16x16x4_f32 v[232:235], v252, v72, v[232:235]
	v_mfma_f32_16x16x4_f32 v[232:235], v253, v73, v[232:235]
	v_mfma_f32_16x16x4_f32 v[232:235], v254, v116, v[232:235]
	v_mfma_f32_16x16x4_f32 v[232:235], v255, v118, v[232:235]
	s_nop 7
	s_nop 3
	ds_write_b32 v243, v220 offset:8192
	ds_write_b32 v243, v221 offset:10240
	ds_write_b32 v243, v222 offset:12288
	ds_write_b32 v243, v223 offset:14336
	ds_write_b32 v243, v224 offset:8256
	ds_write_b32 v243, v225 offset:10304
	ds_write_b32 v243, v226 offset:12352
	ds_write_b32 v243, v227 offset:14400
	ds_write_b32 v243, v228 offset:8320
	ds_write_b32 v243, v229 offset:10368
	ds_write_b32 v243, v230 offset:12416
	ds_write_b32 v243, v231 offset:14464
	ds_write_b32 v243, v232 offset:8384
	ds_write_b32 v243, v233 offset:10432
	ds_write_b32 v243, v234 offset:12480
	ds_write_b32 v243, v235 offset:14528
	s_waitcnt lgkmcnt(0)
.Lmf_skip1:
.LBB0_94:
	s_or_b32 s46, s60, s56
	s_ashr_i32 s47, s46, 31
	s_lshl_b64 s[0:1], s[46:47], 9
	s_or_b32 s2, s60, s59
	v_lshl_add_u64 v[0:1], s[0:1], 0, v[4:5]
	s_mul_i32 s20, s46, 0x3600
	v_lshlrev_b64 v[0:1], 1, v[0:1]
	s_mul_hi_i32 s3, s46, 0x3600
	s_add_u32 s22, s94, s20
	v_lshl_add_u64 v[2:3], s[34:35], 0, v[0:1]
	v_lshl_add_u64 v[0:1], s[62:63], 0, v[0:1]
	s_addc_u32 s23, s95, s3
	v_lshlrev_b64 v[22:23], 1, v[4:5]
	v_sub_co_u32_e64 v139, s[52:53], s2, 1
	global_load_ushort v201, v[2:3], off
	global_load_ushort v202, v[0:1], off
	v_lshl_add_u64 v[0:1], s[22:23], 0, v[22:23]
	s_and_b64 s[24:25], s[52:53], exec
	v_add_co_u32_e32 v18, vcc, s75, v0
	s_cselect_b32 s25, 0, -1
	s_cselect_b32 s24, 0, 0xffffca00
	s_cmp_lt_u32 s2, s57
	v_lshl_add_u64 v[2:3], v[0:1], 0, s[68:69]
	v_addc_co_u32_e32 v19, vcc, 0, v1, vcc
	s_cselect_b64 s[44:45], -1, 0
	global_load_ushort v199, v[18:19], off offset:64
	v_lshl_add_u64 v[18:19], v[2:3], 0, s[24:25]
	s_and_b64 s[24:25], s[44:45], exec
	s_cselect_b32 s28, 0x3600, 0
	v_lshl_add_u64 v[2:3], v[2:3], 0, s[28:29]
	s_lshl_b64 s[24:25], s[46:47], 5
	global_load_ushort v208, v[18:19], off
	global_load_ushort v210, v[2:3], off
	s_add_u32 s24, s10, s24
	v_mov_b32_e32 v19, s1
	v_or_b32_e32 v18, s0, v10
	s_addc_u32 s25, s11, s25
	v_lshlrev_b64 v[18:19], 1, v[18:19]
	s_or_b32 s50, s46, 1
	v_lshl_add_u64 v[20:21], v[6:7], 0, v[18:19]
	v_lshl_add_u64 v[18:19], v[8:9], 0, v[18:19]
	s_ashr_i32 s51, s50, 31
	global_load_ushort v195, v[20:21], off
	global_load_ushort v193, v[18:19], off
	global_load_ushort v196, v[20:21], off offset:128
	global_load_ushort v194, v[18:19], off offset:128
	global_load_ushort v192, v134, s[22:23]
	global_load_ushort v191, v134, s[22:23] offset:128
	v_add_co_u32_e32 v18, vcc, s96, v0
	s_or_b32 s3, s2, 1
	s_lshl_b64 s[0:1], s[50:51], 9
	s_mul_i32 s22, s50, 0x3600
	v_addc_co_u32_e32 v19, vcc, 0, v1, vcc
	s_mul_hi_i32 s20, s50, 0x3600
	s_add_u32 s22, s94, s22
	global_load_ushort v138, v[18:19], off offset:3136
	v_lshl_add_u64 v[18:19], s[0:1], 0, v[4:5]
	s_addc_u32 s23, s95, s20
	v_lshlrev_b64 v[18:19], 1, v[18:19]
	s_cmp_lt_u32 s3, s57
	v_lshl_add_u64 v[20:21], s[34:35], 0, v[18:19]
; __device__ void phase_combine(const P& p, int l, int ntok, float* lds) {
;     ...
;       for (int i = 0; i < 4; ++i) {
;         int row = r0 + i0 + i, t = tb + i0 + i;
;         y0[i] = or0[(size_t)row * 512 + tid]; y1[i] = or1[(size_t)row * 512 + tid];
;         const u16* pv = p.projb + (size_t)row * PROJP + O_RKV + 1024 + tid;
;         vc[i] = pv[0]; vp[i] = pv[t > 0 ? -PROJP : 0]; vn[i] = pv[t < T - 1 ? PROJP : 0];
;         sf[i] = p.sbon[(size_t)row * 8 + wv]; sb[i] = p.sbon[(size_t)NT * 8 + (size_t)row * 8 + wv];
;         size_t ob = (size_t)row * 512 + hh * 128 + lane;
;         a0[i] = om0[ob]; a1[i] = om1[ob]; a2[i] = om0[ob + 64]; a3[i] = om1[ob + 64];
;         const u16* pg = p.projb + (size_t)row * PROJP + gch;
;         g0r[i] = pg[0]; g1r[i] = pg[64];
;         cbr[i] = p.projb[(size_t)row * PROJP + O_CB + tid];
;       }
;       {
;         const u16* pc = p.projb + (size_t)(r0 + i0) * PROJP;
; #pragma unroll
;         for (int j = 0; j < 6; ++j) {
;           int t = tb + i0 + j - 1;
;           int off = (t < 0 ? 0 : (t > T - 1 ? T - 1 : t)) - (tb + i0);
;           const u16* pr = pc + (long)off * PROJP;
;           ucc[j] = pr[O_CC + tid]; uch[j] = pr[O_CH + tid];
;         }
	v_lshl_add_u64 v[18:19], s[62:63], 0, v[18:19]
	s_cselect_b64 s[42:43], -1, 0
	v_lshl_add_u64 v[2:3], s[24:25], 0, v[16:17]
	global_load_ushort v212, v[20:21], off
	global_load_ushort v213, v[18:19], off
	v_lshl_add_u64 v[20:21], s[22:23], 0, v[22:23]
	s_and_b64 s[24:25], s[42:43], exec
	v_lshl_add_u64 v[18:19], v[20:21], 0, s[68:69]
	v_add_co_u32_e32 v136, vcc, s75, v20
	s_cselect_b32 s28, 0x3600, 0
	s_nop 0
	v_addc_co_u32_e32 v137, vcc, 0, v21, vcc
	v_lshl_add_u64 v[18:19], v[18:19], 0, s[28:29]
	s_lshl_b64 s[24:25], s[50:51], 5
	global_load_ushort v198, v[136:137], off offset:64
	global_load_ushort v206, v[18:19], off
	s_add_u32 s24, s10, s24
	v_mov_b32_e32 v137, s1
	v_or_b32_e32 v136, s0, v10
	s_addc_u32 s25, s11, s25
	v_lshlrev_b64 v[136:137], 1, v[136:137]
	s_or_b32 s48, s46, 2
	v_lshl_add_u64 v[140:141], v[6:7], 0, v[136:137]
	v_lshl_add_u64 v[136:137], v[8:9], 0, v[136:137]
	s_ashr_i32 s49, s48, 31
	global_load_ushort v167, v[140:141], off
	global_load_ushort v165, v[136:137], off
	global_load_ushort v190, v[140:141], off offset:128
	global_load_ushort v166, v[136:137], off offset:128
	global_load_ushort v164, v134, s[22:23]
	global_load_ushort v163, v134, s[22:23] offset:128
	v_add_co_u32_e32 v20, vcc, s96, v20
	s_or_b32 s23, s2, 2
	s_lshl_b64 s[0:1], s[48:49], 9
	s_mul_i32 s22, s48, 0x3600
	v_lshl_add_u64 v[18:19], s[24:25], 0, v[16:17]
	v_addc_co_u32_e32 v21, vcc, 0, v21, vcc
	s_mul_hi_i32 s20, s48, 0x3600
	s_add_u32 s24, s94, s22
	global_load_ushort v137, v[20:21], off offset:3136
	v_lshl_add_u64 v[20:21], s[0:1], 0, v[4:5]
	s_addc_u32 s25, s95, s20
	v_lshlrev_b64 v[20:21], 1, v[20:21]
	s_cmp_lt_u32 s23, s57
	v_lshl_add_u64 v[140:141], s[34:35], 0, v[20:21]
	v_lshl_add_u64 v[20:21], s[62:63], 0, v[20:21]
	s_cselect_b64 s[40:41], -1, 0
	global_load_ushort v209, v[140:141], off
	global_load_ushort v211, v[20:21], off
	v_lshl_add_u64 v[140:141], s[24:25], 0, v[22:23]
	s_and_b64 s[26:27], s[40:41], exec
	v_lshl_add_u64 v[20:21], v[140:141], 0, s[68:69]
	v_add_co_u32_e32 v142, vcc, s75, v140
	s_cselect_b32 s28, 0x3600, 0
	s_lshl_b64 s[26:27], s[48:49], 5
	v_addc_co_u32_e32 v143, vcc, 0, v141, vcc
	v_lshl_add_u64 v[20:21], v[20:21], 0, s[28:29]
	s_add_u32 s26, s10, s26
	global_load_ushort v197, v[142:143], off offset:64
	global_load_ushort v204, v[20:21], off
	s_addc_u32 s27, s11, s27
	v_mov_b32_e32 v143, s1
	v_or_b32_e32 v142, s0, v10
	s_or_b32 s36, s46, 3
	v_lshlrev_b64 v[142:143], 1, v[142:143]
	v_add_co_u32_e32 v140, vcc, s96, v140
	s_ashr_i32 s37, s36, 31
	v_lshl_add_u64 v[144:145], v[6:7], 0, v[142:143]
	v_lshl_add_u64 v[142:143], v[8:9], 0, v[142:143]
	v_addc_co_u32_e32 v141, vcc, 0, v141, vcc
	s_lshl_b64 s[0:1], s[36:37], 9
	v_lshl_add_u64 v[20:21], s[26:27], 0, v[16:17]
	global_load_ushort v161, v[144:145], off
	global_load_ushort v159, v[142:143], off
	global_load_ushort v162, v[144:145], off offset:128
	global_load_ushort v160, v[142:143], off offset:128
	global_load_ushort v158, v134, s[24:25]
	global_load_ushort v157, v134, s[24:25] offset:128
	global_load_ushort v136, v[140:141], off offset:3136
	s_or_b32 s26, s2, 3
	v_lshl_add_u64 v[140:141], s[0:1], 0, v[4:5]
	s_mul_i32 s22, s36, 0x3600
	v_lshlrev_b64 v[140:141], 1, v[140:141]
	s_mul_hi_i32 s20, s36, 0x3600
	s_add_u32 s24, s94, s22
	v_lshl_add_u64 v[142:143], s[34:35], 0, v[140:141]
	v_lshl_add_u64 v[140:141], s[62:63], 0, v[140:141]
	s_addc_u32 s25, s95, s20
	global_load_ushort v205, v[142:143], off
	global_load_ushort v207, v[140:141], off
	v_lshl_add_u64 v[140:141], s[24:25], 0, v[22:23]
	v_add_co_u32_e32 v142, vcc, s75, v140
	s_cmp_lt_u32 s26, s57
	s_nop 0
	v_addc_co_u32_e32 v143, vcc, 0, v141, vcc
	s_cselect_b64 vcc, -1, 0
	s_and_b64 s[30:31], vcc, exec
	v_lshl_add_u64 v[22:23], v[140:141], 0, s[68:69]
	s_cselect_b32 s28, 0x3600, 0
	v_lshl_add_u64 v[22:23], v[22:23], 0, s[28:29]
	global_load_ushort v200, v[142:143], off offset:64
	global_load_ushort v203, v[22:23], off
	v_mov_b32_e32 v143, s1
	v_or_b32_e32 v142, s0, v10
	v_min_i32_e32 v139, s57, v139
	v_lshlrev_b64 v[142:143], 1, v[142:143]
	v_add_co_u32_e64 v140, s[0:1], s96, v140
	v_cndmask_b32_e64 v139, v139, 0, s[52:53]
	v_lshl_add_u64 v[144:145], v[6:7], 0, v[142:143]
	v_lshl_add_u64 v[142:143], v[8:9], 0, v[142:143]
	v_addc_co_u32_e64 v141, s[0:1], 0, v141, s[0:1]
	v_subrev_u32_e32 v139, s2, v139
	global_load_ushort v155, v[144:145], off
	global_load_ushort v153, v[142:143], off
	global_load_ushort v156, v[144:145], off offset:128
	global_load_ushort v154, v[142:143], off offset:128
	global_load_ushort v152, v134, s[24:25]
	global_load_ushort v149, v134, s[24:25] offset:128
	global_load_ushort v135, v[140:141], off offset:3136
	v_mad_i64_i32 v[140:141], s[0:1], v139, s61, v[0:1]
	v_add_co_u32_e64 v140, s[0:1], s78, v140
	s_lshl_b64 s[30:31], s[36:37], 5
	s_nop 0
	v_addc_co_u32_e64 v141, s[0:1], 0, v141, s[0:1]
	global_load_ushort v139, v[140:141], off offset:64
	s_nop 0
	global_load_ushort v140, v[140:141], off offset:1088
	v_mov_b32_e32 v141, s57
	v_sub_u32_e64 v141, s2, v141 clamp
	v_sub_u32_e32 v141, 0, v141
	v_mad_i64_i32 v[142:143], s[0:1], v141, s61, v[0:1]
	v_add_co_u32_e64 v142, s[0:1], s78, v142
	s_add_u32 s30, s10, s30
	s_nop 0
	v_addc_co_u32_e64 v143, s[0:1], 0, v143, s[0:1]
	s_addc_u32 s31, s11, s31
	s_min_u32 s0, s3, s57
	s_sub_i32 s0, s0, s2
	global_load_ushort v147, v[142:143], off offset:64
	global_load_ushort v148, v[142:143], off offset:1088
	v_mad_i64_i32 v[142:143], s[0:1], s0, v179, v[0:1]
	v_add_co_u32_e64 v142, s[0:1], s78, v142
	v_lshl_add_u64 v[22:23], s[30:31], 0, v[16:17]
	s_nop 0
	v_addc_co_u32_e64 v143, s[0:1], 0, v143, s[0:1]
	s_min_u32 s0, s23, s57
	s_sub_i32 s0, s0, s2
	global_load_ushort v150, v[142:143], off offset:64
	global_load_ushort v151, v[142:143], off offset:1088
	v_mad_i64_i32 v[142:143], s[0:1], s0, v179, v[0:1]
	v_add_co_u32_e64 v142, s[0:1], s78, v142
	s_waitcnt vmcnt(25)
; #define PIN8(a, o) asm volatile("" : "+v"(a[o]), "+v"(a[o + 1]), "+v"(a[o + 2]), "+v"(a[o + 3]), "+v"(a[o + 4]), "+v"(a[o + 5]), "+v"(a[o + 6]), "+v"(a[o + 7]))
; #define PIN8(a) asm volatile("" : "+v"(a[0]), "+v"(a[1]), "+v"(a[2]), "+v"(a[3]))
; __device__ void phase_combine(const P& p, int l, int ntok, float* lds) {
;     ...
; #pragma unroll
;         for (int j = 0; j < 6; ++j) {
;           int t = tb + i0 + j - 1;
;           int off = (t < 0 ? 0 : (t > T - 1 ? T - 1 : t)) - (tb + i0);
;           const u16* pr = pc + (long)off * PROJP;
;           ucc[j] = pr[O_CC + tid]; uch[j] = pr[O_CH + tid];
;         }
;       }
;       PIN8(y0); PIN8(y1); PIN8(sf); PIN8(sb); PIN8(a0); PIN8(a1); PIN8(a2); PIN8(a3);
;       PIN8(vc); PIN8(vp); PIN8(vn); PIN8(g0r); PIN8(g1r); PIN8(cbr); PIN8(ucc); PIN8(uch);
;       asm volatile("" : "+v"(ucc[4]), "+v"(ucc[5]), "+v"(uch[4]), "+v"(uch[5]));
;       {
;         float gate[4];
; #pragma unroll
;         for (int i = 0; i < 4; ++i) gate[i] = 0.f;
; #pragma unroll
;         for (int m = 0; m < 96; m += 4) {
; #pragma unroll
;           for (int i = 0; i < 4; ++i) {
;             float4 s = *reinterpret_cast<const float4*>(sig + (i0 + i) * 96 + m);
;             gate[i] += s.x * g2r[m] + s.y * g2r[m + 1] + s.z * g2r[m + 2] + s.w * g2r[m + 3];
;           }
;         }
	v_mov_b32_e32 v216, v197
	v_addc_co_u32_e64 v143, s[0:1], 0, v143, s[0:1]
	s_min_u32 s0, s26, s57
	s_sub_i32 s0, s0, s2
	global_load_ushort v145, v[142:143], off offset:64
	global_load_ushort v146, v[142:143], off offset:1088
	v_mad_i64_i32 v[142:143], s[0:1], s0, v179, v[0:1]
	v_add_co_u32_e64 v214, s[0:1], s78, v142
	s_nop 1
	v_addc_co_u32_e64 v215, s[0:1], 0, v143, s[0:1]
	s_add_i32 s0, s2, 4
	s_min_u32 s0, s0, s57
	s_sub_i32 s0, s0, s2
	v_mad_i64_i32 v[0:1], s[0:1], s0, v179, v[0:1]
	v_add_co_u32_e64 v0, s[0:1], s78, v0
	global_load_ushort v143, v[214:215], off offset:64
	global_load_ushort v144, v[214:215], off offset:1088
	v_addc_co_u32_e64 v1, s[0:1], 0, v1, s[0:1]
	global_load_ushort v141, v[0:1], off offset:64
	global_load_ushort v142, v[0:1], off offset:1088
	global_load_dword v218, v[2:3], off
	global_load_dword v214, v[22:23], off
	global_load_dword v215, v[20:21], off
	global_load_dword v217, v[18:19], off
	v_add_co_u32_e64 v0, s[0:1], s66, v2
	s_lshl_b64 s[2:3], s[48:49], 12
	s_nop 0
	v_addc_co_u32_e64 v1, s[0:1], 0, v3, s[0:1]
	global_load_dword v219, v[0:1], off
	v_add_co_u32_e64 v0, s[0:1], s66, v22
	s_nop 1
	v_addc_co_u32_e64 v1, s[0:1], 0, v23, s[0:1]
	global_load_dword v22, v[0:1], off
	v_add_co_u32_e64 v0, s[0:1], s66, v20
	s_nop 1
	v_addc_co_u32_e64 v1, s[0:1], 0, v21, s[0:1]
	global_load_dword v23, v[0:1], off
	v_add_co_u32_e64 v0, s[0:1], s66, v18
	v_mov_b32_e32 v21, v198
	s_nop 0
	v_addc_co_u32_e64 v1, s[0:1], 0, v19, s[0:1]
	s_mul_i32 s0, s60, 0x180
	s_add_i32 s0, s0, 0
	global_load_dword v20, v[0:1], off
	v_mov_b32_e32 v18, v199
	v_mov_b32_e32 v19, s0
	s_cmp_lt_u32 s98, 4
	s_cbranch_scc1 .Lmf_skip2
	s_cmp_eq_u32 s60, 0
	s_cbranch_scc0 .Lmf_skip2
	v_and_b32_e32 v241, 15, v168
	v_bfe_u32 v242, v168, 4, 2
	v_mul_u32_u24_e32 v241, 0x184, v241
	v_mul_u32_u24_e32 v243, 0x1fc0, v242
	v_lshl_add_u32 v241, v242, 2, v241
	v_lshl_add_u32 v243, v168, 2, v243
	ds_read_b32 v244, v241
	ds_read_b32 v245, v241 offset:16
	ds_read_b32 v246, v241 offset:32
	ds_read_b32 v247, v241 offset:48
	ds_read_b32 v248, v241 offset:64
	ds_read_b32 v249, v241 offset:80
	ds_read_b32 v250, v241 offset:96
	ds_read_b32 v251, v241 offset:112
	ds_read_b32 v252, v241 offset:128
	ds_read_b32 v253, v241 offset:144
	ds_read_b32 v254, v241 offset:160
	ds_read_b32 v255, v241 offset:176
	s_waitcnt lgkmcnt(0)
	v_mfma_f32_16x16x4_f32 v[220:223], v244, v90, 0
	v_mfma_f32_16x16x4_f32 v[220:223], v245, v33, v[220:223]
	v_mfma_f32_16x16x4_f32 v[220:223], v246, v80, v[220:223]
	v_mfma_f32_16x16x4_f32 v[220:223], v247, v83, v[220:223]
	v_mfma_f32_16x16x4_f32 v[220:223], v248, v86, v[220:223]
	v_mfma_f32_16x16x4_f32 v[220:223], v249, v89, v[220:223]
	v_mfma_f32_16x16x4_f32 v[220:223], v250, v25, v[220:223]
	v_mfma_f32_16x16x4_f32 v[220:223], v251, v96, v[220:223]
	v_mfma_f32_16x16x4_f32 v[220:223], v252, v97, v[220:223]
	v_mfma_f32_16x16x4_f32 v[220:223], v253, v98, v[220:223]
	v_mfma_f32_16x16x4_f32 v[220:223], v254, v99, v[220:223]
	v_mfma_f32_16x16x4_f32 v[220:223], v255, v100, v[220:223]
	v_mfma_f32_16x16x4_f32 v[224:227], v244, v91, 0
	v_mfma_f32_16x16x4_f32 v[224:227], v245, v78, v[224:227]
	v_mfma_f32_16x16x4_f32 v[224:227], v246, v81, v[224:227]
	v_mfma_f32_16x16x4_f32 v[224:227], v247, v84, v[224:227]
	v_mfma_f32_16x16x4_f32 v[224:227], v248, v87, v[224:227]
	v_mfma_f32_16x16x4_f32 v[224:227], v249, v26, v[224:227]
	v_mfma_f32_16x16x4_f32 v[224:227], v250, v30, v[224:227]
	v_mfma_f32_16x16x4_f32 v[224:227], v251, v34, v[224:227]
	v_mfma_f32_16x16x4_f32 v[224:227], v252, v38, v[224:227]
	v_mfma_f32_16x16x4_f32 v[224:227], v253, v42, v[224:227]
	v_mfma_f32_16x16x4_f32 v[224:227], v254, v46, v[224:227]
	v_mfma_f32_16x16x4_f32 v[224:227], v255, v50, v[224:227]
	v_mfma_f32_16x16x4_f32 v[228:231], v244, v32, 0
	v_mfma_f32_16x16x4_f32 v[228:231], v245, v79, v[228:231]
	v_mfma_f32_16x16x4_f32 v[228:231], v246, v82, v[228:231]
	v_mfma_f32_16x16x4_f32 v[228:231], v247, v85, v[228:231]
	v_mfma_f32_16x16x4_f32 v[228:231], v248, v88, v[228:231]
	v_mfma_f32_16x16x4_f32 v[228:231], v249, v27, v[228:231]
	v_mfma_f32_16x16x4_f32 v[228:231], v250, v31, v[228:231]
	v_mfma_f32_16x16x4_f32 v[228:231], v251, v35, v[228:231]
	v_mfma_f32_16x16x4_f32 v[228:231], v252, v39, v[228:231]
	v_mfma_f32_16x16x4_f32 v[228:231], v253, v43, v[228:231]
	v_mfma_f32_16x16x4_f32 v[228:231], v254, v47, v[228:231]
	v_mfma_f32_16x16x4_f32 v[228:231], v255, v51, v[228:231]
	v_mfma_f32_16x16x4_f32 v[232:235], v244, v92, 0
	v_mfma_f32_16x16x4_f32 v[232:235], v245, v93, v[232:235]
	v_mfma_f32_16x16x4_f32 v[232:235], v246, v11, v[232:235]
	v_mfma_f32_16x16x4_f32 v[232:235], v247, v94, v[232:235]
	v_mfma_f32_16x16x4_f32 v[232:235], v248, v95, v[232:235]
	v_mfma_f32_16x16x4_f32 v[232:235], v249, v24, v[232:235]
	v_mfma_f32_16x16x4_f32 v[232:235], v250, v103, v[232:235]
	v_mfma_f32_16x16x4_f32 v[232:235], v251, v28, v[232:235]
	v_mfma_f32_16x16x4_f32 v[232:235], v252, v29, v[232:235]
	v_mfma_f32_16x16x4_f32 v[232:235], v253, v36, v[232:235]
	v_mfma_f32_16x16x4_f32 v[232:235], v254, v37, v[232:235]
	v_mfma_f32_16x16x4_f32 v[232:235], v255, v40, v[232:235]
	ds_read_b32 v244, v241 offset:192
	ds_read_b32 v245, v241 offset:208
	ds_read_b32 v246, v241 offset:224
	ds_read_b32 v247, v241 offset:240
	ds_read_b32 v248, v241 offset:256
	ds_read_b32 v249, v241 offset:272
	ds_read_b32 v250, v241 offset:288
	ds_read_b32 v251, v241 offset:304
	ds_read_b32 v252, v241 offset:320
	ds_read_b32 v253, v241 offset:336
	ds_read_b32 v254, v241 offset:352
	ds_read_b32 v255, v241 offset:368
	s_waitcnt lgkmcnt(0)
; __device__ void phase_combine(const P& p, int l, int ntok, float* lds) {
;     ...
; #pragma unroll
;         for (int m = 0; m < 96; m += 4) {
; #pragma unroll
;           for (int i = 0; i < 4; ++i) {
;             float4 s = *reinterpret_cast<const float4*>(sig + (i0 + i) * 96 + m);
;             gate[i] += s.x * g2r[m] + s.y * g2r[m + 1] + s.z * g2r[m + 2] + s.w * g2r[m + 3];
;           }
;         }
	v_mfma_f32_16x16x4_f32 v[220:223], v244, v101, v[220:223]
	v_mfma_f32_16x16x4_f32 v[220:223], v245, v102, v[220:223]
	v_mfma_f32_16x16x4_f32 v[220:223], v246, v45, v[220:223]
	v_mfma_f32_16x16x4_f32 v[220:223], v247, v52, v[220:223]
	v_mfma_f32_16x16x4_f32 v[220:223], v248, v59, v[220:223]
	v_mfma_f32_16x16x4_f32 v[220:223], v249, v66, v[220:223]
	v_mfma_f32_16x16x4_f32 v[220:223], v250, v71, v[220:223]
	v_mfma_f32_16x16x4_f32 v[220:223], v251, v104, v[220:223]
	v_mfma_f32_16x16x4_f32 v[220:223], v252, v107, v[220:223]
	v_mfma_f32_16x16x4_f32 v[220:223], v253, v110, v[220:223]
	v_mfma_f32_16x16x4_f32 v[220:223], v254, v76, v[220:223]
	v_mfma_f32_16x16x4_f32 v[220:223], v255, v114, v[220:223]
	v_mfma_f32_16x16x4_f32 v[224:227], v244, v56, v[224:227]
	v_mfma_f32_16x16x4_f32 v[224:227], v245, v60, v[224:227]
	v_mfma_f32_16x16x4_f32 v[224:227], v246, v48, v[224:227]
	v_mfma_f32_16x16x4_f32 v[224:227], v247, v53, v[224:227]
	v_mfma_f32_16x16x4_f32 v[224:227], v248, v64, v[224:227]
	v_mfma_f32_16x16x4_f32 v[224:227], v249, v67, v[224:227]
	v_mfma_f32_16x16x4_f32 v[224:227], v250, v74, v[224:227]
	v_mfma_f32_16x16x4_f32 v[224:227], v251, v105, v[224:227]
	v_mfma_f32_16x16x4_f32 v[224:227], v252, v108, v[224:227]
	v_mfma_f32_16x16x4_f32 v[224:227], v253, v111, v[224:227]
	v_mfma_f32_16x16x4_f32 v[224:227], v254, v77, v[224:227]
	v_mfma_f32_16x16x4_f32 v[224:227], v255, v115, v[224:227]
	v_mfma_f32_16x16x4_f32 v[228:231], v244, v57, v[228:231]
	v_mfma_f32_16x16x4_f32 v[228:231], v245, v61, v[228:231]
	v_mfma_f32_16x16x4_f32 v[228:231], v246, v49, v[228:231]
	v_mfma_f32_16x16x4_f32 v[228:231], v247, v58, v[228:231]
	v_mfma_f32_16x16x4_f32 v[228:231], v248, v65, v[228:231]
	v_mfma_f32_16x16x4_f32 v[228:231], v249, v70, v[228:231]
	v_mfma_f32_16x16x4_f32 v[228:231], v250, v75, v[228:231]
	v_mfma_f32_16x16x4_f32 v[228:231], v251, v106, v[228:231]
	v_mfma_f32_16x16x4_f32 v[228:231], v252, v109, v[228:231]
	v_mfma_f32_16x16x4_f32 v[228:231], v253, v112, v[228:231]
	v_mfma_f32_16x16x4_f32 v[228:231], v254, v113, v[228:231]
	v_mfma_f32_16x16x4_f32 v[228:231], v255, v117, v[228:231]
	v_mfma_f32_16x16x4_f32 v[232:235], v244, v41, v[232:235]
	v_mfma_f32_16x16x4_f32 v[232:235], v245, v44, v[232:235]
	v_mfma_f32_16x16x4_f32 v[232:235], v246, v54, v[232:235]
	v_mfma_f32_16x16x4_f32 v[232:235], v247, v55, v[232:235]
	v_mfma_f32_16x16x4_f32 v[232:235], v248, v62, v[232:235]
	v_mfma_f32_16x16x4_f32 v[232:235], v249, v63, v[232:235]
	v_mfma_f32_16x16x4_f32 v[232:235], v250, v68, v[232:235]
	v_mfma_f32_16x16x4_f32 v[232:235], v251, v69, v[232:235]
	v_mfma_f32_16x16x4_f32 v[232:235], v252, v72, v[232:235]
	v_mfma_f32_16x16x4_f32 v[232:235], v253, v73, v[232:235]
	v_mfma_f32_16x16x4_f32 v[232:235], v254, v116, v[232:235]
	v_mfma_f32_16x16x4_f32 v[232:235], v255, v118, v[232:235]
	s_nop 7
	s_nop 3
	ds_write_b32 v243, v220 offset:8192
	ds_write_b32 v243, v221 offset:10240
	ds_write_b32 v243, v222 offset:12288
	ds_write_b32 v243, v223 offset:14336
	ds_write_b32 v243, v224 offset:8256
	ds_write_b32 v243, v225 offset:10304
	ds_write_b32 v243, v226 offset:12352
	ds_write_b32 v243, v227 offset:14400
	ds_write_b32 v243, v228 offset:8320
	ds_write_b32 v243, v229 offset:10368
	ds_write_b32 v243, v230 offset:12416
	ds_write_b32 v243, v231 offset:14464
	ds_write_b32 v243, v232 offset:8384
	ds_write_b32 v243, v233 offset:10432
	ds_write_b32 v243, v234 offset:12480
	ds_write_b32 v243, v235 offset:14528
	s_waitcnt lgkmcnt(0)
